# C1 + double-buffered sgemm_sample K-loops (decode rows) in phases 6/7/9/11
# speedup vs baseline: 1.0003x; 1.0003x over previous
; #define LAS __attribute__((address_space(3)))
; __device__ __forceinline__ int opaque_tid() { int t = threadIdx.x; asm volatile("" : "+v"(t)); return t; }
; template <int MODE>
; __device__ __forceinline__ void sgemm_sample(LAS unsigned char* lds, const bf16_t* A, const bf16_t* Bt, int K, const float* resid, float* out, bf16_t* xb, float* ssq_out, const float* ssq_in) {
;     const int tid = opaque_tid(), lane = tid & 63, w = __builtin_amdgcn_readfirstlane(tid >> 6), fr = lane & 15, fq = lane >> 4;
;     const int u = blockIdx.x * 8 + w;
;     const bool act = (gridDim.x == 256);
; #pragma unroll 1
;     for (int uu = u; uu < 2048; uu += gridDim.x * 8) {
;         const int rt = uu >> 6, ct = uu & 63; const int row = NTOKP + rt * 16 + fr, col0 = ct * 16 + fq * 4;
;         const bf16_t* ap = A + (size_t)row * K + fq * 8; const bf16_t* bp = Bt + (size_t)(ct * 16 + fr) * K + fq * 8;
;         f32x4 acc = {0.f, 0.f, 0.f, 0.f};
; #pragma unroll 8
;         for (int ks = 0; ks < K / 32; ++ks) {
;             const bf16x8 a = *(const bf16x8*)(ap + ks * 32); const bf16x8 b = *(const bf16x8*)(bp + ks * 32);
;             acc = __builtin_amdgcn_mfma_f32_16x16x32_bf16(b, a, acc, 0, 0, 0);
;         }
.LBB0_895:
	v_lshl_add_u64 v[192:193], v[14:15], 0, s[16:17]
	v_lshl_add_u64 v[194:195], v[10:11], 0, s[16:17]
	v_add_co_u32_e32 v196, vcc, 0x15780000, v192
	s_nop 1
	v_addc_co_u32_e32 v197, vcc, 0, v193, vcc
	v_add_co_u32_e32 v198, vcc, 0x840000, v194
	s_nop 1
	v_addc_co_u32_e32 v199, vcc, 0, v195, vcc
	global_load_dwordx4 v[64:67], v[196:197], off
	global_load_dwordx4 v[96:99], v[198:199], off
	global_load_dwordx4 v[68:71], v[196:197], off offset:64
	global_load_dwordx4 v[100:103], v[198:199], off offset:64
	global_load_dwordx4 v[72:75], v[196:197], off offset:128
	global_load_dwordx4 v[104:107], v[198:199], off offset:128
	global_load_dwordx4 v[76:79], v[196:197], off offset:192
	global_load_dwordx4 v[108:111], v[198:199], off offset:192
	global_load_dwordx4 v[80:83], v[196:197], off offset:256
	global_load_dwordx4 v[112:115], v[198:199], off offset:256
	global_load_dwordx4 v[84:87], v[196:197], off offset:320
	global_load_dwordx4 v[116:119], v[198:199], off offset:320
	global_load_dwordx4 v[88:91], v[196:197], off offset:384
	global_load_dwordx4 v[120:123], v[198:199], off offset:384
	global_load_dwordx4 v[92:95], v[196:197], off offset:448
	global_load_dwordx4 v[124:127], v[198:199], off offset:448
.Lsgk0_loop:
	s_add_u32 s16, s16, 0x200
	s_addc_u32 s17, s17, 0
	s_cmpk_eq_i32 s16, 0x800
	s_cbranch_scc1 .Lsgk0_last0
	v_lshl_add_u64 v[192:193], v[14:15], 0, s[16:17]
	v_lshl_add_u64 v[194:195], v[10:11], 0, s[16:17]
	v_add_co_u32_e32 v196, vcc, 0x15780000, v192
	s_nop 1
	v_addc_co_u32_e32 v197, vcc, 0, v193, vcc
	v_add_co_u32_e32 v198, vcc, 0x840000, v194
	s_nop 1
	v_addc_co_u32_e32 v199, vcc, 0, v195, vcc
	global_load_dwordx4 v[128:131], v[196:197], off
	global_load_dwordx4 v[160:163], v[198:199], off
	global_load_dwordx4 v[132:135], v[196:197], off offset:64
	global_load_dwordx4 v[164:167], v[198:199], off offset:64
	global_load_dwordx4 v[136:139], v[196:197], off offset:128
	global_load_dwordx4 v[168:171], v[198:199], off offset:128
	global_load_dwordx4 v[140:143], v[196:197], off offset:192
	global_load_dwordx4 v[172:175], v[198:199], off offset:192
	global_load_dwordx4 v[144:147], v[196:197], off offset:256
	global_load_dwordx4 v[176:179], v[198:199], off offset:256
	global_load_dwordx4 v[148:151], v[196:197], off offset:320
	global_load_dwordx4 v[180:183], v[198:199], off offset:320
	global_load_dwordx4 v[152:155], v[196:197], off offset:384
	global_load_dwordx4 v[184:187], v[198:199], off offset:384
	global_load_dwordx4 v[156:159], v[196:197], off offset:448
	global_load_dwordx4 v[188:191], v[198:199], off offset:448
	s_waitcnt vmcnt(16)
	v_mfma_f32_16x16x32_bf16 v[0:3], v[96:99], v[64:67], v[0:3]
	v_mfma_f32_16x16x32_bf16 v[0:3], v[100:103], v[68:71], v[0:3]
	v_mfma_f32_16x16x32_bf16 v[0:3], v[104:107], v[72:75], v[0:3]
	v_mfma_f32_16x16x32_bf16 v[0:3], v[108:111], v[76:79], v[0:3]
	v_mfma_f32_16x16x32_bf16 v[0:3], v[112:115], v[80:83], v[0:3]
	v_mfma_f32_16x16x32_bf16 v[0:3], v[116:119], v[84:87], v[0:3]
	v_mfma_f32_16x16x32_bf16 v[0:3], v[120:123], v[88:91], v[0:3]
	v_mfma_f32_16x16x32_bf16 v[0:3], v[124:127], v[92:95], v[0:3]
	s_add_u32 s16, s16, 0x200
	s_addc_u32 s17, s17, 0
	s_cmpk_eq_i32 s16, 0x800
	s_cbranch_scc1 .Lsgk0_last1
	v_lshl_add_u64 v[192:193], v[14:15], 0, s[16:17]
	v_lshl_add_u64 v[194:195], v[10:11], 0, s[16:17]
	v_add_co_u32_e32 v196, vcc, 0x15780000, v192
	s_nop 1
	v_addc_co_u32_e32 v197, vcc, 0, v193, vcc
	v_add_co_u32_e32 v198, vcc, 0x840000, v194
	s_nop 1
	v_addc_co_u32_e32 v199, vcc, 0, v195, vcc
	global_load_dwordx4 v[64:67], v[196:197], off
	global_load_dwordx4 v[96:99], v[198:199], off
	global_load_dwordx4 v[68:71], v[196:197], off offset:64
	global_load_dwordx4 v[100:103], v[198:199], off offset:64
	global_load_dwordx4 v[72:75], v[196:197], off offset:128
	global_load_dwordx4 v[104:107], v[198:199], off offset:128
	global_load_dwordx4 v[76:79], v[196:197], off offset:192
	global_load_dwordx4 v[108:111], v[198:199], off offset:192
	global_load_dwordx4 v[80:83], v[196:197], off offset:256
	global_load_dwordx4 v[112:115], v[198:199], off offset:256
	global_load_dwordx4 v[84:87], v[196:197], off offset:320
	global_load_dwordx4 v[116:119], v[198:199], off offset:320
	global_load_dwordx4 v[88:91], v[196:197], off offset:384
	global_load_dwordx4 v[120:123], v[198:199], off offset:384
	global_load_dwordx4 v[92:95], v[196:197], off offset:448
	global_load_dwordx4 v[124:127], v[198:199], off offset:448
	s_waitcnt vmcnt(16)
	v_mfma_f32_16x16x32_bf16 v[0:3], v[160:163], v[128:131], v[0:3]
	v_mfma_f32_16x16x32_bf16 v[0:3], v[164:167], v[132:135], v[0:3]
	v_mfma_f32_16x16x32_bf16 v[0:3], v[168:171], v[136:139], v[0:3]
	v_mfma_f32_16x16x32_bf16 v[0:3], v[172:175], v[140:143], v[0:3]
	v_mfma_f32_16x16x32_bf16 v[0:3], v[176:179], v[144:147], v[0:3]
	v_mfma_f32_16x16x32_bf16 v[0:3], v[180:183], v[148:151], v[0:3]
	v_mfma_f32_16x16x32_bf16 v[0:3], v[184:187], v[152:155], v[0:3]
	v_mfma_f32_16x16x32_bf16 v[0:3], v[188:191], v[156:159], v[0:3]
	s_branch .Lsgk0_loop
; #define LAS __attribute__((address_space(3)))
; __device__ __forceinline__ unsigned cvt_pk_bf16(float lo, float hi) { f32x2 f = {lo, hi}; bf16x2_t v = __builtin_convertvector(f, bf16x2_t); return __builtin_bit_cast(unsigned, v); }
; template <int MODE>
; __device__ __forceinline__ void sgemm_sample(LAS unsigned char* lds, const bf16_t* A, const bf16_t* Bt, int K, const float* resid, float* out, bf16_t* xb, float* ssq_out, const float* ssq_in) {
;     ...
;         for (int ks = 0; ks < K / 32; ++ks) {
;             const bf16x8 a = *(const bf16x8*)(ap + ks * 32); const bf16x8 b = *(const bf16x8*)(bp + ks * 32);
;             acc = __builtin_amdgcn_mfma_f32_16x16x32_bf16(b, a, acc, 0, 0, 0);
;         }
;         if (MODE == 0) {
;             const f32x4 x = *(const f32x4*)(resid + (size_t)(row - NTOKP) * D + col0) + acc;
;             *(f32x4*)(out + (size_t)row * D + col0) = x;
;             if (xb) { u32x2 wv; wv.x = cvt_pk_bf16(x[0], x[1]); wv.y = cvt_pk_bf16(x[2], x[3]); *(u32x2*)(xb + (size_t)row * D + col0) = wv; }
;             if (ssq_out) {
;                 float ss = (x[0] * x[0] + x[1] * x[1]) + (x[2] * x[2] + x[3] * x[3]); ss += __shfl_xor(ss, 16); ss += __shfl_xor(ss, 32);
;                 if (fq == 0) *(LAS float*)(lds + (w * 16 + fr) * 4) = ss;
;                 __syncthreads();
;                 if (tid < 16) { float t = 0.f;
; #pragma unroll
;                     for (int i = 0; i < 8; ++i) t += *(const LAS float*)(lds + (i * 16 + tid) * 4);
;                     const int g = (uu & 63) >> 3; float* sp = ssq_out + (size_t)(NTOKP + rt * 16 + tid) * 16; sp[g] = t; sp[8 + g] = 0.f; }
;                 __syncthreads();
;             }
.Lsgk0_last0:
	s_waitcnt vmcnt(0)
	v_mfma_f32_16x16x32_bf16 v[0:3], v[96:99], v[64:67], v[0:3]
	v_mfma_f32_16x16x32_bf16 v[0:3], v[100:103], v[68:71], v[0:3]
	v_mfma_f32_16x16x32_bf16 v[0:3], v[104:107], v[72:75], v[0:3]
	v_mfma_f32_16x16x32_bf16 v[0:3], v[108:111], v[76:79], v[0:3]
	v_mfma_f32_16x16x32_bf16 v[0:3], v[112:115], v[80:83], v[0:3]
	v_mfma_f32_16x16x32_bf16 v[0:3], v[116:119], v[84:87], v[0:3]
	v_mfma_f32_16x16x32_bf16 v[0:3], v[120:123], v[88:91], v[0:3]
	v_mfma_f32_16x16x32_bf16 v[0:3], v[124:127], v[92:95], v[0:3]
	s_branch .Lsgk0_done
.Lsgk0_last1:
	s_waitcnt vmcnt(0)
	v_mfma_f32_16x16x32_bf16 v[0:3], v[160:163], v[128:131], v[0:3]
	v_mfma_f32_16x16x32_bf16 v[0:3], v[164:167], v[132:135], v[0:3]
	v_mfma_f32_16x16x32_bf16 v[0:3], v[168:171], v[136:139], v[0:3]
	v_mfma_f32_16x16x32_bf16 v[0:3], v[172:175], v[140:143], v[0:3]
	v_mfma_f32_16x16x32_bf16 v[0:3], v[176:179], v[144:147], v[0:3]
	v_mfma_f32_16x16x32_bf16 v[0:3], v[180:183], v[148:151], v[0:3]
	v_mfma_f32_16x16x32_bf16 v[0:3], v[184:187], v[152:155], v[0:3]
	v_mfma_f32_16x16x32_bf16 v[0:3], v[188:191], v[156:159], v[0:3]
.Lsgk0_done:
	s_nop 7
	s_and_b32 s18, s3, 63
	v_lshl_or_b32 v24, s18, 4, v18
	v_lshlrev_b64 v[14:15], 12, v[12:13]
	v_lshl_add_u64 v[10:11], s[40:41], 0, v[14:15]
	v_lshlrev_b32_e32 v4, 2, v24
	v_lshl_add_u64 v[10:11], v[10:11], 0, v[4:5]
	v_add_co_u32_e32 v10, vcc, 0xf8000000, v10
	v_lshl_add_u64 v[14:15], s[90:91], 0, v[14:15]
	s_nop 0
	v_addc_co_u32_e32 v11, vcc, -1, v11, vcc
	global_load_dwordx4 v[10:13], v[10:11], off
	s_waitcnt vmcnt(0)
	v_pk_add_f32 v[2:3], v[2:3], v[12:13]
	v_pk_add_f32 v[0:1], v[0:1], v[10:11]
	v_mul_f32_e32 v11, v3, v3
	v_mul_f32_e32 v10, v1, v1
	v_fmac_f32_e32 v10, v0, v0
	v_fmac_f32_e32 v11, v2, v2
	v_add_f32_e32 v12, v10, v11
	ds_bpermute_b32 v13, v19, v12
	v_lshl_add_u64 v[10:11], v[14:15], 0, v[4:5]
	global_store_dwordx4 v[10:11], v[0:3], off
	v_cvt_pk_bf16_f32 v10, v0, v1
	v_cvt_pk_bf16_f32 v11, v2, v3
	s_waitcnt lgkmcnt(0)
	v_add_f32_e32 v0, v12, v13
	ds_bpermute_b32 v1, v20, v0
	v_lshl_add_u64 v[2:3], s[10:11], 0, v[8:9]
	v_lshlrev_b32_e32 v4, 1, v24
	v_lshl_add_u64 v[2:3], v[2:3], 0, v[4:5]
	global_store_dwordx2 v[2:3], v[10:11], off
	s_and_saveexec_b64 s[16:17], s[0:1]
	s_cbranch_execz .LBB0_898
	s_waitcnt lgkmcnt(0)
	v_add_f32_e32 v0, v0, v1
	ds_write_b32 v22, v0

; template <int MODE>
; __device__ __forceinline__ void sgemm_sample(LAS unsigned char* lds, const bf16_t* A, const bf16_t* Bt, int K, const float* resid, float* out, bf16_t* xb, float* ssq_out, const float* ssq_in) {
;     ...
;         const bf16_t* ap = A + (size_t)row * K + fq * 8; const bf16_t* bp = Bt + (size_t)(ct * 16 + fr) * K + fq * 8;
;         f32x4 acc = {0.f, 0.f, 0.f, 0.f};
; #pragma unroll 8
;         for (int ks = 0; ks < K / 32; ++ks) {
;             const bf16x8 a = *(const bf16x8*)(ap + ks * 32); const bf16x8 b = *(const bf16x8*)(bp + ks * 32);
;             acc = __builtin_amdgcn_mfma_f32_16x16x32_bf16(b, a, acc, 0, 0, 0);
;         }
.LBB0_1000:
	v_lshl_add_u64 v[192:193], v[14:15], 0, s[0:1]
	v_lshl_add_u64 v[194:195], v[12:13], 0, s[0:1]
	v_add_co_u32_e32 v196, vcc, 0xa4c0000, v192
	s_nop 1
	v_addc_co_u32_e32 v197, vcc, 0, v193, vcc
	v_add_co_u32_e32 v198, vcc, 0xa40000, v194
	s_nop 1
	v_addc_co_u32_e32 v199, vcc, 0, v195, vcc
	global_load_dwordx4 v[64:67], v[196:197], off
	global_load_dwordx4 v[96:99], v[198:199], off
	global_load_dwordx4 v[68:71], v[196:197], off offset:64
	global_load_dwordx4 v[100:103], v[198:199], off offset:64
	global_load_dwordx4 v[72:75], v[196:197], off offset:128
	global_load_dwordx4 v[104:107], v[198:199], off offset:128
	global_load_dwordx4 v[76:79], v[196:197], off offset:192
	global_load_dwordx4 v[108:111], v[198:199], off offset:192
	global_load_dwordx4 v[80:83], v[196:197], off offset:256
	global_load_dwordx4 v[112:115], v[198:199], off offset:256
	global_load_dwordx4 v[84:87], v[196:197], off offset:320
	global_load_dwordx4 v[116:119], v[198:199], off offset:320
	global_load_dwordx4 v[88:91], v[196:197], off offset:384
	global_load_dwordx4 v[120:123], v[198:199], off offset:384
	global_load_dwordx4 v[92:95], v[196:197], off offset:448
	global_load_dwordx4 v[124:127], v[198:199], off offset:448
.Lsgk1_loop:
	s_add_u32 s0, s0, 0x200
	s_addc_u32 s1, s1, 0
	s_cmpk_eq_i32 s0, 0x800
	s_cbranch_scc1 .Lsgk1_last0
	v_lshl_add_u64 v[192:193], v[14:15], 0, s[0:1]
	v_lshl_add_u64 v[194:195], v[12:13], 0, s[0:1]
	v_add_co_u32_e32 v196, vcc, 0xa4c0000, v192
	s_nop 1
	v_addc_co_u32_e32 v197, vcc, 0, v193, vcc
	v_add_co_u32_e32 v198, vcc, 0xa40000, v194
	s_nop 1
	v_addc_co_u32_e32 v199, vcc, 0, v195, vcc
	global_load_dwordx4 v[128:131], v[196:197], off
	global_load_dwordx4 v[160:163], v[198:199], off
	global_load_dwordx4 v[132:135], v[196:197], off offset:64
	global_load_dwordx4 v[164:167], v[198:199], off offset:64
	global_load_dwordx4 v[136:139], v[196:197], off offset:128
	global_load_dwordx4 v[168:171], v[198:199], off offset:128
	global_load_dwordx4 v[140:143], v[196:197], off offset:192
	global_load_dwordx4 v[172:175], v[198:199], off offset:192
	global_load_dwordx4 v[144:147], v[196:197], off offset:256
	global_load_dwordx4 v[176:179], v[198:199], off offset:256
	global_load_dwordx4 v[148:151], v[196:197], off offset:320
	global_load_dwordx4 v[180:183], v[198:199], off offset:320
	global_load_dwordx4 v[152:155], v[196:197], off offset:384
	global_load_dwordx4 v[184:187], v[198:199], off offset:384
	global_load_dwordx4 v[156:159], v[196:197], off offset:448
	global_load_dwordx4 v[188:191], v[198:199], off offset:448
	s_waitcnt vmcnt(16)
	v_mfma_f32_16x16x32_bf16 v[0:3], v[96:99], v[64:67], v[0:3]
	v_mfma_f32_16x16x32_bf16 v[0:3], v[100:103], v[68:71], v[0:3]
	v_mfma_f32_16x16x32_bf16 v[0:3], v[104:107], v[72:75], v[0:3]
	v_mfma_f32_16x16x32_bf16 v[0:3], v[108:111], v[76:79], v[0:3]
	v_mfma_f32_16x16x32_bf16 v[0:3], v[112:115], v[80:83], v[0:3]
	v_mfma_f32_16x16x32_bf16 v[0:3], v[116:119], v[84:87], v[0:3]
	v_mfma_f32_16x16x32_bf16 v[0:3], v[120:123], v[88:91], v[0:3]
	v_mfma_f32_16x16x32_bf16 v[0:3], v[124:127], v[92:95], v[0:3]
	s_add_u32 s0, s0, 0x200
	s_addc_u32 s1, s1, 0
	s_cmpk_eq_i32 s0, 0x800
	s_cbranch_scc1 .Lsgk1_last1
	v_lshl_add_u64 v[192:193], v[14:15], 0, s[0:1]
	v_lshl_add_u64 v[194:195], v[12:13], 0, s[0:1]
	v_add_co_u32_e32 v196, vcc, 0xa4c0000, v192
	s_nop 1
	v_addc_co_u32_e32 v197, vcc, 0, v193, vcc
	v_add_co_u32_e32 v198, vcc, 0xa40000, v194
	s_nop 1
	v_addc_co_u32_e32 v199, vcc, 0, v195, vcc
	global_load_dwordx4 v[64:67], v[196:197], off
	global_load_dwordx4 v[96:99], v[198:199], off
	global_load_dwordx4 v[68:71], v[196:197], off offset:64
	global_load_dwordx4 v[100:103], v[198:199], off offset:64
	global_load_dwordx4 v[72:75], v[196:197], off offset:128
	global_load_dwordx4 v[104:107], v[198:199], off offset:128
	global_load_dwordx4 v[76:79], v[196:197], off offset:192
	global_load_dwordx4 v[108:111], v[198:199], off offset:192
	global_load_dwordx4 v[80:83], v[196:197], off offset:256
	global_load_dwordx4 v[112:115], v[198:199], off offset:256
	global_load_dwordx4 v[84:87], v[196:197], off offset:320
	global_load_dwordx4 v[116:119], v[198:199], off offset:320
	global_load_dwordx4 v[88:91], v[196:197], off offset:384
	global_load_dwordx4 v[120:123], v[198:199], off offset:384
	global_load_dwordx4 v[92:95], v[196:197], off offset:448
	global_load_dwordx4 v[124:127], v[198:199], off offset:448
	s_waitcnt vmcnt(16)
	v_mfma_f32_16x16x32_bf16 v[0:3], v[160:163], v[128:131], v[0:3]
	v_mfma_f32_16x16x32_bf16 v[0:3], v[164:167], v[132:135], v[0:3]
	v_mfma_f32_16x16x32_bf16 v[0:3], v[168:171], v[136:139], v[0:3]
	v_mfma_f32_16x16x32_bf16 v[0:3], v[172:175], v[140:143], v[0:3]
	v_mfma_f32_16x16x32_bf16 v[0:3], v[176:179], v[144:147], v[0:3]
	v_mfma_f32_16x16x32_bf16 v[0:3], v[180:183], v[148:151], v[0:3]
	v_mfma_f32_16x16x32_bf16 v[0:3], v[184:187], v[152:155], v[0:3]
	v_mfma_f32_16x16x32_bf16 v[0:3], v[188:191], v[156:159], v[0:3]
	s_branch .Lsgk1_loop

; __device__ __forceinline__ unsigned cvt_pk_bf16(float lo, float hi) { f32x2 f = {lo, hi}; bf16x2_t v = __builtin_convertvector(f, bf16x2_t); return __builtin_bit_cast(unsigned, v); }
; template <int MODE>
; __device__ __forceinline__ void sgemm_sample(LAS unsigned char* lds, const bf16_t* A, const bf16_t* Bt, int K, const float* resid, float* out, bf16_t* xb, float* ssq_out, const float* ssq_in) {
;     ...
;         } else {
;             const float sc = rs_from_parts(ssq_in + (size_t)row * 16) * 0.0625f;
;             u32x2 wv; wv.x = cvt_pk_bf16(acc[0] * sc, acc[1] * sc); wv.y = cvt_pk_bf16(acc[2] * sc, acc[3] * sc); *(u32x2*)(xb + (size_t)row * D + col0) = wv;
;         }
.Lsgk1_done:
	s_nop 7
	v_lshlrev_b64 v[10:11], 6, v[10:11]
	v_lshl_add_u64 v[14:15], s[4:5], 0, v[10:11]
	global_load_dwordx4 v[10:13], v[14:15], off
	global_load_dwordx4 v[20:23], v[14:15], off offset:16
	global_load_dwordx4 v[24:27], v[14:15], off offset:32
	global_load_dwordx4 v[28:31], v[14:15], off offset:48
	s_lshl_b32 s0, s3, 4
	s_and_b32 s0, s0, 0x3f0
	v_lshl_add_u64 v[8:9], s[10:11], 0, v[8:9]
	s_add_i32 s3, s3, s6
	s_add_i32 s7, s7, s12
	s_cmpk_gt_i32 s3, 0x7ff
	s_waitcnt vmcnt(3)
	v_mov_b32_e32 v14, v11
	v_mov_b32_e32 v15, v12
	v_mov_b32_e32 v11, v13
	s_waitcnt vmcnt(2)
	v_mov_b32_e32 v12, v21
	v_mov_b32_e32 v13, v22
	v_mov_b32_e32 v21, v23
	v_pk_add_f32 v[10:11], v[14:15], v[10:11]
	v_pk_add_f32 v[12:13], v[12:13], v[20:21]
	v_pk_add_f32 v[10:11], v[10:11], v[10:11] op_sel:[0,1] op_sel_hi:[1,0]
	v_pk_add_f32 v[12:13], v[12:13], v[12:13] op_sel:[0,1] op_sel_hi:[1,0]
	s_waitcnt vmcnt(1)
	v_add_f32_e32 v22, v24, v25
	v_add_f32_e32 v24, v26, v27
	s_waitcnt vmcnt(0)
	v_mov_b32_e32 v23, v30
	v_mov_b32_e32 v25, v31
	v_mov_b32_e32 v11, v28
	v_mov_b32_e32 v13, v29
	v_pk_add_f32 v[14:15], v[22:23], v[24:25]
	v_pk_add_f32 v[10:11], v[10:11], v[12:13]
	s_nop 0
	v_pk_add_f32 v[10:11], v[10:11], v[14:15]
	s_nop 0
	v_add_f32_e32 v4, v10, v11
	v_fmamk_f32 v4, v4, 0x3a800000, v19
	v_mul_f32_e32 v10, 0x4b800000, v4
	v_cmp_gt_f32_e32 vcc, s13, v4
	s_nop 1
	v_cndmask_b32_e32 v4, v4, v10, vcc
	v_rsq_f32_e32 v10, v4
	v_or_b32_e32 v4, s0, v17
	v_lshlrev_b32_e32 v4, 1, v4
	v_lshl_add_u64 v[8:9], v[8:9], 0, v[4:5]
	v_mul_f32_e32 v4, 0x45800000, v10
	v_cndmask_b32_e32 v4, v10, v4, vcc
	v_mul_f32_e32 v4, 0x3d800000, v4
	v_pk_mul_f32 v[0:1], v[0:1], v[4:5] op_sel_hi:[1,0]
	v_pk_mul_f32 v[2:3], v[2:3], v[4:5] op_sel_hi:[1,0]
	v_cvt_pk_bf16_f32 v0, v0, v1
	v_cvt_pk_bf16_f32 v1, v2, v3
	global_store_dwordx2 v[8:9], v[0:1], off
	s_cbranch_scc0 .LBB0_999

; template <int MODE>
; __device__ __forceinline__ void sgemm_sample(LAS unsigned char* lds, const bf16_t* A, const bf16_t* Bt, int K, const float* resid, float* out, bf16_t* xb, float* ssq_out, const float* ssq_in) {
;     ...
;         const bf16_t* ap = A + (size_t)row * K + fq * 8; const bf16_t* bp = Bt + (size_t)(ct * 16 + fr) * K + fq * 8;
;         f32x4 acc = {0.f, 0.f, 0.f, 0.f};
; #pragma unroll 8
;         for (int ks = 0; ks < K / 32; ++ks) {
;             const bf16x8 a = *(const bf16x8*)(ap + ks * 32); const bf16x8 b = *(const bf16x8*)(bp + ks * 32);
;             acc = __builtin_amdgcn_mfma_f32_16x16x32_bf16(b, a, acc, 0, 0, 0);
;         }
.LBB0_1169:
	v_lshl_add_u64 v[192:193], v[14:15], 0, s[18:19]
	v_lshl_add_u64 v[194:195], v[10:11], 0, s[18:19]
	v_add_co_u32_e32 v196, vcc, 0x15780000, v192
	s_nop 1
	v_addc_co_u32_e32 v197, vcc, 0, v193, vcc
	v_add_co_u32_e32 v198, vcc, 0x1040000, v194
	s_nop 1
	v_addc_co_u32_e32 v199, vcc, 0, v195, vcc
	global_load_dwordx4 v[64:67], v[196:197], off
	global_load_dwordx4 v[96:99], v[198:199], off
	global_load_dwordx4 v[68:71], v[196:197], off offset:64
	global_load_dwordx4 v[100:103], v[198:199], off offset:64
	global_load_dwordx4 v[72:75], v[196:197], off offset:128
	global_load_dwordx4 v[104:107], v[198:199], off offset:128
	global_load_dwordx4 v[76:79], v[196:197], off offset:192
	global_load_dwordx4 v[108:111], v[198:199], off offset:192
	global_load_dwordx4 v[80:83], v[196:197], off offset:256
	global_load_dwordx4 v[112:115], v[198:199], off offset:256
	global_load_dwordx4 v[84:87], v[196:197], off offset:320
	global_load_dwordx4 v[116:119], v[198:199], off offset:320
	global_load_dwordx4 v[88:91], v[196:197], off offset:384
	global_load_dwordx4 v[120:123], v[198:199], off offset:384
	global_load_dwordx4 v[92:95], v[196:197], off offset:448
	global_load_dwordx4 v[124:127], v[198:199], off offset:448
.Lsgk2_loop:
	s_add_u32 s18, s18, 0x200
	s_addc_u32 s19, s19, 0
	s_cmpk_eq_i32 s18, 0x800
	s_cbranch_scc1 .Lsgk2_last0
	v_lshl_add_u64 v[192:193], v[14:15], 0, s[18:19]
	v_lshl_add_u64 v[194:195], v[10:11], 0, s[18:19]
	v_add_co_u32_e32 v196, vcc, 0x15780000, v192
	s_nop 1
	v_addc_co_u32_e32 v197, vcc, 0, v193, vcc
	v_add_co_u32_e32 v198, vcc, 0x1040000, v194
	s_nop 1
	v_addc_co_u32_e32 v199, vcc, 0, v195, vcc
	global_load_dwordx4 v[128:131], v[196:197], off
	global_load_dwordx4 v[160:163], v[198:199], off
	global_load_dwordx4 v[132:135], v[196:197], off offset:64
	global_load_dwordx4 v[164:167], v[198:199], off offset:64
	global_load_dwordx4 v[136:139], v[196:197], off offset:128
	global_load_dwordx4 v[168:171], v[198:199], off offset:128
	global_load_dwordx4 v[140:143], v[196:197], off offset:192
	global_load_dwordx4 v[172:175], v[198:199], off offset:192
	global_load_dwordx4 v[144:147], v[196:197], off offset:256
	global_load_dwordx4 v[176:179], v[198:199], off offset:256
	global_load_dwordx4 v[148:151], v[196:197], off offset:320
	global_load_dwordx4 v[180:183], v[198:199], off offset:320
	global_load_dwordx4 v[152:155], v[196:197], off offset:384
	global_load_dwordx4 v[184:187], v[198:199], off offset:384
	global_load_dwordx4 v[156:159], v[196:197], off offset:448
	global_load_dwordx4 v[188:191], v[198:199], off offset:448
	s_waitcnt vmcnt(16)
	v_mfma_f32_16x16x32_bf16 v[0:3], v[96:99], v[64:67], v[0:3]
	v_mfma_f32_16x16x32_bf16 v[0:3], v[100:103], v[68:71], v[0:3]
	v_mfma_f32_16x16x32_bf16 v[0:3], v[104:107], v[72:75], v[0:3]
	v_mfma_f32_16x16x32_bf16 v[0:3], v[108:111], v[76:79], v[0:3]
	v_mfma_f32_16x16x32_bf16 v[0:3], v[112:115], v[80:83], v[0:3]
	v_mfma_f32_16x16x32_bf16 v[0:3], v[116:119], v[84:87], v[0:3]
	v_mfma_f32_16x16x32_bf16 v[0:3], v[120:123], v[88:91], v[0:3]
	v_mfma_f32_16x16x32_bf16 v[0:3], v[124:127], v[92:95], v[0:3]
	s_add_u32 s18, s18, 0x200
	s_addc_u32 s19, s19, 0
	s_cmpk_eq_i32 s18, 0x800
	s_cbranch_scc1 .Lsgk2_last1
	v_lshl_add_u64 v[192:193], v[14:15], 0, s[18:19]
	v_lshl_add_u64 v[194:195], v[10:11], 0, s[18:19]
	v_add_co_u32_e32 v196, vcc, 0x15780000, v192
	s_nop 1
	v_addc_co_u32_e32 v197, vcc, 0, v193, vcc
	v_add_co_u32_e32 v198, vcc, 0x1040000, v194
	s_nop 1
	v_addc_co_u32_e32 v199, vcc, 0, v195, vcc
	global_load_dwordx4 v[64:67], v[196:197], off
	global_load_dwordx4 v[96:99], v[198:199], off
	global_load_dwordx4 v[68:71], v[196:197], off offset:64
	global_load_dwordx4 v[100:103], v[198:199], off offset:64
	global_load_dwordx4 v[72:75], v[196:197], off offset:128
	global_load_dwordx4 v[104:107], v[198:199], off offset:128
	global_load_dwordx4 v[76:79], v[196:197], off offset:192
	global_load_dwordx4 v[108:111], v[198:199], off offset:192
	global_load_dwordx4 v[80:83], v[196:197], off offset:256
	global_load_dwordx4 v[112:115], v[198:199], off offset:256
	global_load_dwordx4 v[84:87], v[196:197], off offset:320
	global_load_dwordx4 v[116:119], v[198:199], off offset:320
	global_load_dwordx4 v[88:91], v[196:197], off offset:384
	global_load_dwordx4 v[120:123], v[198:199], off offset:384
	global_load_dwordx4 v[92:95], v[196:197], off offset:448
	global_load_dwordx4 v[124:127], v[198:199], off offset:448
	s_waitcnt vmcnt(16)
	v_mfma_f32_16x16x32_bf16 v[0:3], v[160:163], v[128:131], v[0:3]
	v_mfma_f32_16x16x32_bf16 v[0:3], v[164:167], v[132:135], v[0:3]
	v_mfma_f32_16x16x32_bf16 v[0:3], v[168:171], v[136:139], v[0:3]
	v_mfma_f32_16x16x32_bf16 v[0:3], v[172:175], v[140:143], v[0:3]
	v_mfma_f32_16x16x32_bf16 v[0:3], v[176:179], v[144:147], v[0:3]
	v_mfma_f32_16x16x32_bf16 v[0:3], v[180:183], v[148:151], v[0:3]
	v_mfma_f32_16x16x32_bf16 v[0:3], v[184:187], v[152:155], v[0:3]
	v_mfma_f32_16x16x32_bf16 v[0:3], v[188:191], v[156:159], v[0:3]
	s_branch .Lsgk2_loop

; #define LAS __attribute__((address_space(3)))
; __device__ __forceinline__ unsigned cvt_pk_bf16(float lo, float hi) { f32x2 f = {lo, hi}; bf16x2_t v = __builtin_convertvector(f, bf16x2_t); return __builtin_bit_cast(unsigned, v); }
; template <int MODE>
; __device__ __forceinline__ void sgemm_sample(LAS unsigned char* lds, const bf16_t* A, const bf16_t* Bt, int K, const float* resid, float* out, bf16_t* xb, float* ssq_out, const float* ssq_in) {
;     ...
;         if (MODE == 0) {
;             const f32x4 x = *(const f32x4*)(resid + (size_t)(row - NTOKP) * D + col0) + acc;
;             *(f32x4*)(out + (size_t)row * D + col0) = x;
;             if (xb) { u32x2 wv; wv.x = cvt_pk_bf16(x[0], x[1]); wv.y = cvt_pk_bf16(x[2], x[3]); *(u32x2*)(xb + (size_t)row * D + col0) = wv; }
;             if (ssq_out) {
;                 float ss = (x[0] * x[0] + x[1] * x[1]) + (x[2] * x[2] + x[3] * x[3]); ss += __shfl_xor(ss, 16); ss += __shfl_xor(ss, 32);
;                 if (fq == 0) *(LAS float*)(lds + (w * 16 + fr) * 4) = ss;
;                 __syncthreads();
;                 if (tid < 16) { float t = 0.f;
; #pragma unroll
;                     for (int i = 0; i < 8; ++i) t += *(const LAS float*)(lds + (i * 16 + tid) * 4);
;                     const int g = (uu & 63) >> 3; float* sp = ssq_out + (size_t)(NTOKP + rt * 16 + tid) * 16; sp[g] = t; sp[8 + g] = 0.f; }
;                 __syncthreads();
;             }
.Lsgk2_done:
	s_nop 7
	s_and_b32 s20, s3, 63
	v_lshl_or_b32 v24, s20, 4, v18
	v_lshlrev_b64 v[14:15], 12, v[12:13]
	v_lshl_add_u64 v[10:11], s[10:11], 0, v[14:15]
	v_lshlrev_b32_e32 v4, 2, v24
	v_lshl_add_u64 v[10:11], v[10:11], 0, v[4:5]
	v_add_co_u32_e32 v10, vcc, 0xf8000000, v10
	v_lshl_add_u64 v[14:15], s[90:91], 0, v[14:15]
	s_nop 0
	v_addc_co_u32_e32 v11, vcc, -1, v11, vcc
	global_load_dwordx4 v[10:13], v[10:11], off
	s_waitcnt vmcnt(0)
	v_pk_add_f32 v[2:3], v[2:3], v[12:13]
	v_pk_add_f32 v[0:1], v[0:1], v[10:11]
	v_mul_f32_e32 v11, v3, v3
	v_mul_f32_e32 v10, v1, v1
	v_fmac_f32_e32 v10, v0, v0
	v_fmac_f32_e32 v11, v2, v2
	v_add_f32_e32 v12, v10, v11
	ds_bpermute_b32 v13, v19, v12
	v_lshl_add_u64 v[10:11], v[14:15], 0, v[4:5]
	global_store_dwordx4 v[10:11], v[0:3], off
	v_cvt_pk_bf16_f32 v10, v0, v1
	v_cvt_pk_bf16_f32 v11, v2, v3
	s_waitcnt lgkmcnt(0)
	v_add_f32_e32 v0, v12, v13
	ds_bpermute_b32 v1, v20, v0
	v_lshl_add_u64 v[2:3], s[12:13], 0, v[8:9]
	v_lshlrev_b32_e32 v4, 1, v24
	v_lshl_add_u64 v[2:3], v[2:3], 0, v[4:5]
	global_store_dwordx2 v[2:3], v[10:11], off
	s_and_saveexec_b64 s[18:19], s[0:1]
	s_cbranch_execz .LBB0_1172
	s_waitcnt lgkmcnt(0)
	v_add_f32_e32 v0, v0, v1
	ds_write_b32 v22, v0

; template <int MODE>
; __device__ __forceinline__ void sgemm_sample(LAS unsigned char* lds, const bf16_t* A, const bf16_t* Bt, int K, const float* resid, float* out, bf16_t* xb, float* ssq_out, const float* ssq_in) {
;     ...
;         const bf16_t* ap = A + (size_t)row * K + fq * 8; const bf16_t* bp = Bt + (size_t)(ct * 16 + fr) * K + fq * 8;
;         f32x4 acc = {0.f, 0.f, 0.f, 0.f};
; #pragma unroll 8
;         for (int ks = 0; ks < K / 32; ++ks) {
;             const bf16x8 a = *(const bf16x8*)(ap + ks * 32); const bf16x8 b = *(const bf16x8*)(bp + ks * 32);
;             acc = __builtin_amdgcn_mfma_f32_16x16x32_bf16(b, a, acc, 0, 0, 0);
;         }
.LBB0_1349:
	v_lshl_add_u64 v[192:193], v[10:11], 0, s[0:1]
	v_lshl_add_u64 v[194:195], v[12:13], 0, s[0:1]
	v_add_co_u32_e32 v196, vcc, 0x22c0000, v192
	s_nop 1
	v_addc_co_u32_e32 v197, vcc, 0, v193, vcc
	v_add_co_u32_e32 v198, vcc, 0x1d40000, v194
	s_nop 1
	v_addc_co_u32_e32 v199, vcc, 0, v195, vcc
	global_load_dwordx4 v[64:67], v[196:197], off
	global_load_dwordx4 v[96:99], v[198:199], off
	global_load_dwordx4 v[68:71], v[196:197], off offset:64
	global_load_dwordx4 v[100:103], v[198:199], off offset:64
	global_load_dwordx4 v[72:75], v[196:197], off offset:128
	global_load_dwordx4 v[104:107], v[198:199], off offset:128
	global_load_dwordx4 v[76:79], v[196:197], off offset:192
	global_load_dwordx4 v[108:111], v[198:199], off offset:192
	global_load_dwordx4 v[80:83], v[196:197], off offset:256
	global_load_dwordx4 v[112:115], v[198:199], off offset:256
	global_load_dwordx4 v[84:87], v[196:197], off offset:320
	global_load_dwordx4 v[116:119], v[198:199], off offset:320
	global_load_dwordx4 v[88:91], v[196:197], off offset:384
	global_load_dwordx4 v[120:123], v[198:199], off offset:384
	global_load_dwordx4 v[92:95], v[196:197], off offset:448
	global_load_dwordx4 v[124:127], v[198:199], off offset:448
.Lsgk3_loop:
	s_add_u32 s0, s0, 0x200
	s_addc_u32 s1, s1, 0
	s_cmpk_eq_i32 s0, 0x1600
	s_cbranch_scc1 .Lsgk3_last0
	v_lshl_add_u64 v[192:193], v[10:11], 0, s[0:1]
	v_lshl_add_u64 v[194:195], v[12:13], 0, s[0:1]
	v_add_co_u32_e32 v196, vcc, 0x22c0000, v192
	s_nop 1
	v_addc_co_u32_e32 v197, vcc, 0, v193, vcc
	v_add_co_u32_e32 v198, vcc, 0x1d40000, v194
	s_nop 1
	v_addc_co_u32_e32 v199, vcc, 0, v195, vcc
	global_load_dwordx4 v[128:131], v[196:197], off
	global_load_dwordx4 v[160:163], v[198:199], off
	global_load_dwordx4 v[132:135], v[196:197], off offset:64
	global_load_dwordx4 v[164:167], v[198:199], off offset:64
	global_load_dwordx4 v[136:139], v[196:197], off offset:128
	global_load_dwordx4 v[168:171], v[198:199], off offset:128
	global_load_dwordx4 v[140:143], v[196:197], off offset:192
	global_load_dwordx4 v[172:175], v[198:199], off offset:192
	global_load_dwordx4 v[144:147], v[196:197], off offset:256
	global_load_dwordx4 v[176:179], v[198:199], off offset:256
	global_load_dwordx4 v[148:151], v[196:197], off offset:320
	global_load_dwordx4 v[180:183], v[198:199], off offset:320
	global_load_dwordx4 v[152:155], v[196:197], off offset:384
	global_load_dwordx4 v[184:187], v[198:199], off offset:384
	global_load_dwordx4 v[156:159], v[196:197], off offset:448
	global_load_dwordx4 v[188:191], v[198:199], off offset:448
	s_waitcnt vmcnt(16)
	v_mfma_f32_16x16x32_bf16 v[0:3], v[96:99], v[64:67], v[0:3]
	v_mfma_f32_16x16x32_bf16 v[0:3], v[100:103], v[68:71], v[0:3]
	v_mfma_f32_16x16x32_bf16 v[0:3], v[104:107], v[72:75], v[0:3]
	v_mfma_f32_16x16x32_bf16 v[0:3], v[108:111], v[76:79], v[0:3]
	v_mfma_f32_16x16x32_bf16 v[0:3], v[112:115], v[80:83], v[0:3]
	v_mfma_f32_16x16x32_bf16 v[0:3], v[116:119], v[84:87], v[0:3]
	v_mfma_f32_16x16x32_bf16 v[0:3], v[120:123], v[88:91], v[0:3]
	v_mfma_f32_16x16x32_bf16 v[0:3], v[124:127], v[92:95], v[0:3]
	s_add_u32 s0, s0, 0x200
	s_addc_u32 s1, s1, 0
	s_cmpk_eq_i32 s0, 0x1600
	s_cbranch_scc1 .Lsgk3_last1
	v_lshl_add_u64 v[192:193], v[10:11], 0, s[0:1]
	v_lshl_add_u64 v[194:195], v[12:13], 0, s[0:1]
	v_add_co_u32_e32 v196, vcc, 0x22c0000, v192
	s_nop 1
	v_addc_co_u32_e32 v197, vcc, 0, v193, vcc
	v_add_co_u32_e32 v198, vcc, 0x1d40000, v194
	s_nop 1
	v_addc_co_u32_e32 v199, vcc, 0, v195, vcc
	global_load_dwordx4 v[64:67], v[196:197], off
	global_load_dwordx4 v[96:99], v[198:199], off
	global_load_dwordx4 v[68:71], v[196:197], off offset:64
	global_load_dwordx4 v[100:103], v[198:199], off offset:64
	global_load_dwordx4 v[72:75], v[196:197], off offset:128
	global_load_dwordx4 v[104:107], v[198:199], off offset:128
	global_load_dwordx4 v[76:79], v[196:197], off offset:192
	global_load_dwordx4 v[108:111], v[198:199], off offset:192
	global_load_dwordx4 v[80:83], v[196:197], off offset:256
	global_load_dwordx4 v[112:115], v[198:199], off offset:256
	global_load_dwordx4 v[84:87], v[196:197], off offset:320
	global_load_dwordx4 v[116:119], v[198:199], off offset:320
	global_load_dwordx4 v[88:91], v[196:197], off offset:384
	global_load_dwordx4 v[120:123], v[198:199], off offset:384
	global_load_dwordx4 v[92:95], v[196:197], off offset:448
	global_load_dwordx4 v[124:127], v[198:199], off offset:448
	s_waitcnt vmcnt(16)
	v_mfma_f32_16x16x32_bf16 v[0:3], v[160:163], v[128:131], v[0:3]
	v_mfma_f32_16x16x32_bf16 v[0:3], v[164:167], v[132:135], v[0:3]
	v_mfma_f32_16x16x32_bf16 v[0:3], v[168:171], v[136:139], v[0:3]
	v_mfma_f32_16x16x32_bf16 v[0:3], v[172:175], v[140:143], v[0:3]
	v_mfma_f32_16x16x32_bf16 v[0:3], v[176:179], v[144:147], v[0:3]
	v_mfma_f32_16x16x32_bf16 v[0:3], v[180:183], v[148:151], v[0:3]
	v_mfma_f32_16x16x32_bf16 v[0:3], v[184:187], v[152:155], v[0:3]
	v_mfma_f32_16x16x32_bf16 v[0:3], v[188:191], v[156:159], v[0:3]
	s_branch .Lsgk3_loop

; template <int MODE>
; __device__ __forceinline__ void sgemm_sample(LAS unsigned char* lds, const bf16_t* A, const bf16_t* Bt, int K, const float* resid, float* out, bf16_t* xb, float* ssq_out, const float* ssq_in) {
;     ...
;         if (MODE == 0) {
;             const f32x4 x = *(const f32x4*)(resid + (size_t)(row - NTOKP) * D + col0) + acc;
;             *(f32x4*)(out + (size_t)row * D + col0) = x;
.Lsgk3_done:
	s_nop 7
	v_or_b32_e32 v4, s10, v15
	v_lshlrev_b64 v[12:13], 12, v[8:9]
	v_lshl_add_u64 v[8:9], s[8:9], 0, v[12:13]
	v_lshlrev_b32_e32 v4, 2, v4
	v_lshl_add_u64 v[8:9], v[8:9], 0, v[4:5]
	v_add_co_u32_e32 v8, vcc, 0xf8000000, v8
	s_add_i32 s3, s3, s4
	s_nop 0
	v_addc_co_u32_e32 v9, vcc, -1, v9, vcc
	global_load_dwordx4 v[8:11], v[8:9], off
	v_lshl_add_u64 v[12:13], s[90:91], 0, v[12:13]
	v_lshl_add_u64 v[12:13], v[12:13], 0, v[4:5]
	s_cmpk_gt_i32 s3, 0x7ff
	s_waitcnt vmcnt(0)
	v_pk_add_f32 v[2:3], v[2:3], v[10:11]
	v_pk_add_f32 v[0:1], v[0:1], v[8:9]
	global_store_dwordx4 v[12:13], v[0:3], off
	s_cbranch_scc0 .LBB0_1348
